# stick-breaking attention: V key-block loaded with the K mapping (128 B runs per row) and staged with the K LDS pattern
# speedup vs baseline: 1.0185x; 1.0003x over previous
; #define LAS __attribute__((address_space(3)))
; #define LDS_BAR() do { asm volatile("s_waitcnt lgkmcnt(0)" ::: "memory"); __builtin_amdgcn_s_barrier(); asm volatile("" ::: "memory"); } while (0)
; #define SB_LOAD(kb_) do { _Pragma("unroll") for (int uu = 0; uu < 2; ++uu) { \
;         pkr[uu] = *(const u32x4*)(P0 + (rowbase + (kb_) * 128 + krow + 64 * uu) * AB_IN + 1536 + 64 * h + 8 * kc8); \
;         pvr[uu] = *(const u32x4*)(P0 + (rowbase + (kb_) * 128 + vs_) * AB_IN + 2048 + 64 * h + 8 * (vc8 + 4 * uu)); } } while (0)
; __device__ __forceinline__ void sb_unit(LAS unsigned char* lds, const bf16_t* P0, bf16_t* MIX, int b, int h, int qc) {
;     ...
;     const size_t rowbase = (size_t)b * SEQ; const int q0 = qc * 128, tq = q0 + 16 * w + fr;
;     const bf16_t* qp = P0 + (rowbase + tq) * AB_IN + 1024 + 64 * h + 8 * fq;
;     const bf16x8 qf0 = *(const bf16x8*)qp, qf1 = *(const bf16x8*)(qp + 32);
;     f32x4 oacc[4];
; #pragma unroll
;     for (int n = 0; n < 4; ++n) oacc[n] = (f32x4){0.f, 0.f, 0.f, 0.f};
;     float R = 1.f;
;     LAS unsigned* flags = (LAS unsigned*)(Vl + 128 * 72);
;     u32x4 pkr[2], pvr[2];
;     const int krow = tid >> 3, kc8 = tid & 7, vs_ = tid & 127, vc8 = tid >> 7;
;     ...
;     SB_LOAD(qc);
;     LDS_BAR();
.LBB0_294:
	s_and_b64 vcc, exec, s[0:1]
	s_cbranch_vccz .LBB0_289
	s_ashr_i32 s57, s33, 7
	s_sub_i32 s0, 15, s57
	s_lshl_b32 s1, s33, 8
	s_lshl_b32 s4, s0, 7
	s_and_b32 s52, s1, 0x7800
	v_add_u32_e32 v91, s4, v89
	v_add_u32_e32 v96, s52, v91
	v_mov_b64_e32 v[8:9], s[26:27]
	v_mad_u64_u32 v[0:1], s[0:1], v96, s3, v[8:9]
	s_lshl_b32 s0, s33, 6
	s_add_i32 s4, s4, s52
	s_and_b32 s53, s0, 0x1c0
	v_or_b32_e32 v10, s4, v84
	s_lshl_b32 s22, s53, 1
	s_waitcnt vmcnt(7)
	v_or_b32_e32 v12, s4, v82
	v_mad_u64_u32 v[10:11], s[0:1], v10, s3, v[8:9]
	v_lshl_add_u64 v[10:11], v[10:11], 0, s[22:23]
	v_mad_u64_u32 v[8:9], s[0:1], v12, s3, v[8:9]
	v_lshlrev_b32_e32 v98, 1, v88
	v_mov_b32_e32 v99, v73
	v_lshl_add_u64 v[10:11], v[10:11], 0, v[98:99]
	s_movk_i32 s0, 0x1000
	v_lshl_add_u64 v[8:9], v[8:9], 0, s[22:23]
	v_lshlrev_b32_e32 v72, 1, v86
	s_waitcnt vmcnt(4)
	v_lshl_add_u64 v[24:25], v[10:11], 0, s[18:19]
	v_add_co_u32_e32 v10, vcc, s0, v10
	v_lshl_add_u64 v[8:9], v[8:9], 0, v[72:73]
	s_nop 0
	v_addc_co_u32_e32 v11, vcc, 0, v11, vcc
	v_lshl_add_u64 v[0:1], v[0:1], 0, s[22:23]
	v_mov_b32_e32 v95, v73
	v_add_co_u32_e32 v16, vcc, 0x50000, v8
	v_lshl_add_u64 v[4:5], v[0:1], 0, v[94:95]
	s_nop 0
	v_addc_co_u32_e32 v17, vcc, 0, v9, vcc
	global_load_dwordx4 v[0:3], v[4:5], off offset:2048
	s_nop 0
	global_load_dwordx4 v[4:7], v[4:5], off offset:2112
	s_nop 0
	v_lshl_add_u64 v[10:11], v[8:9], 0, s[18:19]
	v_lshl_add_u64 v[24:25], v[16:17], 0, s[18:19]
	global_load_dwordx4 v[12:15], v[10:11], off
	s_nop 0
	global_load_dwordx4 v[16:19], v[16:17], off offset:3072
	s_nop 0
	global_load_dwordx4 v[20:23], v[8:9], off offset:3072
	s_nop 0
	global_load_dwordx4 v[24:27], v[24:25], off
	s_waitcnt lgkmcnt(0)
	s_barrier
	s_and_b32 s0, s33, 0xffffff80
	v_mov_b32_e32 v8, 0
	v_mov_b32_e32 v97, v73
	s_sub_i32 s56, 0x780, s0
	s_add_i32 s57, s57, -15
	v_mov_b32_e32 v93, 1.0
	v_mov_b32_e32 v95, 0
	v_mov_b32_e32 v9, v8
	v_mov_b32_e32 v10, v8
	v_mov_b32_e32 v11, v8
	v_mov_b32_e32 v28, v8
	v_mov_b32_e32 v29, v8
	v_mov_b32_e32 v30, v8
	v_mov_b32_e32 v31, v8
	v_mov_b32_e32 v32, v8
	v_mov_b32_e32 v33, v8
	v_mov_b32_e32 v34, v8
	v_mov_b32_e32 v35, v8
	v_mov_b32_e32 v36, v8
	v_mov_b32_e32 v37, v8
	v_mov_b32_e32 v38, v8
	v_mov_b32_e32 v39, v8
	s_branch .LBB0_297

; #define LAS __attribute__((address_space(3)))
; #define LDS_BAR() do { asm volatile("s_waitcnt lgkmcnt(0)" ::: "memory"); __builtin_amdgcn_s_barrier(); asm volatile("" ::: "memory"); } while (0)
; #define SB_LOAD(kb_) do { _Pragma("unroll") for (int uu = 0; uu < 2; ++uu) { \
;         pkr[uu] = *(const u32x4*)(P0 + (rowbase + (kb_) * 128 + krow + 64 * uu) * AB_IN + 1536 + 64 * h + 8 * kc8); \
;         pvr[uu] = *(const u32x4*)(P0 + (rowbase + (kb_) * 128 + vs_) * AB_IN + 2048 + 64 * h + 8 * (vc8 + 4 * uu)); } } while (0)
; __device__ __forceinline__ void sb_unit(LAS unsigned char* lds, const bf16_t* P0, bf16_t* MIX, int b, int h, int qc) {
;     ...
; #pragma unroll
;         for (int uu = 0; uu < 2; ++uu) {
;             *(LAS u32x4*)(Ks + (krow + 64 * uu) * 72 + 8 * kc8) = pkr[uu];
;             *(LAS u32x4*)(Vl + vs_ * 72 + 8 * (vc8 + 4 * uu)) = pvr[uu]; }
;         LDS_BAR();
;         if (kb > 0) SB_LOAD(kb - 1);
.LBB0_297:
	s_waitcnt vmcnt(1)
	ds_write_b128 v108, v[20:23]
	ds_write_b128 v108, v[12:15] offset:18432
	ds_write_b128 v108, v[16:19] offset:9216
	s_waitcnt vmcnt(0)
	ds_write_b128 v108, v[24:27] offset:27648
	s_waitcnt lgkmcnt(0)
	s_barrier
	v_cmp_eq_u32_e32 vcc, s57, v95
	s_mov_b32 s0, 0
	s_cbranch_vccnz .LBB0_299
	s_add_i32 s0, s56, s52
	s_addk_i32 s0, 0xff80
	v_or_b32_e32 v16, s0, v82
	v_or_b32_e32 v14, s0, v84
	v_mov_b64_e32 v[12:13], s[26:27]
	v_mad_u64_u32 v[14:15], s[0:1], v14, s3, v[12:13]
	s_lshl_b32 s22, s53, 1
	v_mad_u64_u32 v[12:13], s[0:1], v16, s3, v[12:13]
	v_lshl_add_u64 v[14:15], v[14:15], 0, s[22:23]
	v_lshl_add_u64 v[12:13], v[12:13], 0, s[22:23]
	v_mov_b32_e32 v99, v73
	v_lshl_add_u64 v[20:21], v[12:13], 0, v[72:73]
	v_lshl_add_u64 v[12:13], v[14:15], 0, v[98:99]
	v_lshl_add_u64 v[24:25], v[12:13], 0, s[18:19]
	v_add_co_u32_e32 v12, vcc, 0x1000, v12
	s_mov_b32 s0, s56
	s_nop 0
	v_addc_co_u32_e32 v13, vcc, 0, v13, vcc
	v_add_co_u32_e32 v16, vcc, 0x50000, v20
	s_nop 1
	v_addc_co_u32_e32 v17, vcc, 0, v21, vcc
	v_lshl_add_u64 v[12:13], v[20:21], 0, s[18:19]
	v_lshl_add_u64 v[24:25], v[16:17], 0, s[18:19]
	global_load_dwordx4 v[12:15], v[12:13], off
	s_nop 0
	global_load_dwordx4 v[16:19], v[16:17], off offset:3072
	s_nop 0
	global_load_dwordx4 v[20:23], v[20:21], off offset:3072
	s_nop 0
	global_load_dwordx4 v[24:27], v[24:25], off
